# first seam uses xcd barrier (loop entered at ph=0) instead of cg grid sync
# speedup vs baseline: 1.0565x; 1.0366x over previous
.LBB0_65:
.LBB0_77:
	s_mov_b32 s66, 0
	s_load_dword s67, s[0:1], 0x124
	s_waitcnt lgkmcnt(0)
	s_cmp_ge_i32 s66, s67
	s_cbranch_scc0 .LBB0_78
	s_getpc_b64 s[98:99]
